# scan loops: no-op exec restores removed; v_mov_dpp+v_add folded into v_add_f32_dpp
# baseline (speedup 1.0000x reference)
.LBB0_858:
	v_pk_mul_f32 v[50:51], v[50:51], v[84:85]
	v_pk_mul_f32 v[46:47], v[46:47], v[88:89]
	s_waitcnt lgkmcnt(14)
	v_pk_fma_f32 v[50:51], v[66:67], v[62:63], v[50:51] op_sel_hi:[0,1,1]
	v_pk_fma_f32 v[46:47], v[66:67], v[58:59], v[46:47] op_sel_hi:[0,1,1]
	s_waitcnt lgkmcnt(13)
	v_pk_fma_f32 v[84:85], v[0:1], v[54:55], v[50:51] op_sel_hi:[0,1,1]
	v_pk_mul_f32 v[50:51], v[52:53], v[86:87]
	v_pk_fma_f32 v[88:89], v[0:1], v[42:43], v[46:47] op_sel_hi:[0,1,1]
	v_pk_mul_f32 v[42:43], v[48:49], v[90:91]
	v_pk_fma_f32 v[50:51], v[66:67], v[64:65], v[50:51] op_sel_hi:[0,1,1]
	v_pk_fma_f32 v[42:43], v[66:67], v[60:61], v[42:43] op_sel_hi:[0,1,1]
	s_add_i32 s46, s46, s3
	s_add_i32 s10, s10, 2
	s_addk_i32 s7, 0xc40
	v_pk_fma_f32 v[86:87], v[0:1], v[56:57], v[50:51] op_sel_hi:[0,1,1]
	s_cmp_gt_u32 s10, 13
	v_pk_fma_f32 v[90:91], v[0:1], v[44:45], v[42:43] op_sel_hi:[0,1,1]
	s_cbranch_scc1 .LBB0_863
.LBB0_859:
	s_waitcnt lgkmcnt(0)
	v_mov_b32_e32 v95, v96
	v_add_u32_e32 v96, s7, v100
	ds_read_b128 v[70:73], v96 offset:1568
	ds_read_b128 v[66:69], v96 offset:1584
	ds_read_b128 v[50:53], v96 offset:1824
	ds_read_b128 v[46:49], v96 offset:1840
	ds_read_b128 v[54:57], v96 offset:2080
	ds_read_b128 v[42:45], v96 offset:2096
	ds_read_b128 v[78:81], v96 offset:2336
	ds_read_b128 v[74:77], v96 offset:2352
	ds_read_b128 v[62:65], v96 offset:2592
	ds_read_b128 v[58:61], v96 offset:2608
	v_pk_fma_f32 v[34:35], v[84:85], v[34:35], 0 op_sel_hi:[1,1,0]
	v_pk_fma_f32 v[22:23], v[84:85], v[22:23], 0 op_sel_hi:[1,1,0]
	v_pk_fma_f32 v[34:35], v[86:87], v[36:37], v[34:35]
	v_pk_fma_f32 v[22:23], v[86:87], v[24:25], v[22:23]
	v_add_u32_e32 v103, s7, v102
	v_mov_b32_e32 v98, s7
	v_pk_fma_f32 v[24:25], v[88:89], v[38:39], v[34:35]
	v_pk_fma_f32 v[18:19], v[88:89], v[18:19], v[22:23]
	ds_read_b32 v0, v103 offset:2848
	ds_read_b64 v[98:99], v98 offset:3104
	v_pk_fma_f32 v[22:23], v[90:91], v[40:41], v[24:25]
	v_pk_fma_f32 v[20:21], v[90:91], v[20:21], v[18:19]
	v_add_f32_e32 v18, v22, v23
	v_add_f32_e32 v19, v20, v21
	s_nop 0
	v_add_f32_dpp v18, v18, v18 quad_perm:[1,0,3,2] row_mask:0xf bank_mask:0xf bound_ctrl:1
	v_add_f32_dpp v19, v19, v19 quad_perm:[1,0,3,2] row_mask:0xf bank_mask:0xf bound_ctrl:1
	s_nop 0
	v_add_f32_dpp v18, v18, v18 quad_perm:[2,3,0,1] row_mask:0xf bank_mask:0xf bound_ctrl:1
	v_add_f32_dpp v19, v19, v19 quad_perm:[2,3,0,1] row_mask:0xf bank_mask:0xf bound_ctrl:1
	s_nop 0
	v_add_f32_dpp v18, v18, v18 row_half_mirror row_mask:0xf bank_mask:0xf bound_ctrl:1
	v_mov_b32_e32 v22, v97
	v_mov_b32_e32 v23, v18
	v_pk_mul_f32 v[22:23], v[22:23], v[94:95]
	v_add_f32_dpp v19, v19, v19 row_half_mirror row_mask:0xf bank_mask:0xf bound_ctrl:1
	v_add_f32_e32 v19, v23, v19
	v_add_f32_e32 v19, v22, v19
	s_ashr_i32 s47, s46, 31
	v_bfe_u32 v20, v19, 16, 1
	s_lshl_b64 s[20:21], s[46:47], 9
	v_add3_u32 v19, v19, v20, s28
	v_lshl_add_u64 v[20:21], v[92:93], 0, s[20:21]
	global_store_short_d16_hi v[20:21], v19, off
.LBB0_861:
	v_pk_mul_f32 v[2:3], v[84:85], v[2:3]
	s_nop 0
	v_pk_fma_f32 v[2:3], v[18:19], v[26:27], v[2:3] op_sel_hi:[0,1,1]
	v_pk_fma_f32 v[84:85], v[94:95], v[10:11], v[2:3] op_sel_hi:[0,1,1]
	v_pk_mul_f32 v[2:3], v[86:87], v[4:5]
	s_waitcnt lgkmcnt(5)
	v_pk_fma_f32 v[78:79], v[84:85], v[78:79], 0 op_sel_hi:[1,1,0]
	v_pk_fma_f32 v[2:3], v[18:19], v[28:29], v[2:3] op_sel_hi:[0,1,1]
	v_pk_fma_f32 v[86:87], v[94:95], v[12:13], v[2:3] op_sel_hi:[0,1,1]
	v_pk_mul_f32 v[2:3], v[88:89], v[6:7]
	v_pk_fma_f32 v[70:71], v[84:85], v[70:71], 0 op_sel_hi:[1,1,0]
	v_pk_fma_f32 v[2:3], v[18:19], v[30:31], v[2:3] op_sel_hi:[0,1,1]
	v_pk_fma_f32 v[88:89], v[94:95], v[14:15], v[2:3] op_sel_hi:[0,1,1]
	v_pk_mul_f32 v[2:3], v[90:91], v[8:9]
	v_pk_fma_f32 v[78:79], v[86:87], v[80:81], v[78:79]
	v_pk_fma_f32 v[2:3], v[18:19], v[32:33], v[2:3] op_sel_hi:[0,1,1]
	v_pk_fma_f32 v[90:91], v[94:95], v[16:17], v[2:3] op_sel_hi:[0,1,1]
	ds_read_b128 v[22:25], v96 offset:3136
	ds_read_b128 v[18:21], v96 offset:3152
	ds_read_b128 v[2:5], v96 offset:3392
	ds_read_b128 v[6:9], v96 offset:3408
	ds_read_b128 v[10:13], v96 offset:3648
	ds_read_b128 v[14:17], v96 offset:3664
	ds_read_b128 v[34:37], v96 offset:3904
	ds_read_b128 v[38:41], v96 offset:3920
	ds_read_b128 v[26:29], v96 offset:4160
	ds_read_b128 v[30:33], v96 offset:4176
	v_pk_fma_f32 v[70:71], v[86:87], v[72:73], v[70:71]
	s_waitcnt lgkmcnt(14)
	v_pk_fma_f32 v[72:73], v[88:89], v[74:75], v[78:79]
	v_pk_fma_f32 v[66:67], v[88:89], v[66:67], v[70:71]
	v_mov_b32_e32 v95, s7
	ds_read_b32 v94, v103 offset:4416
	ds_read_b64 v[96:97], v95 offset:4672
	v_pk_fma_f32 v[70:71], v[90:91], v[76:77], v[72:73]
	v_pk_fma_f32 v[68:69], v[90:91], v[68:69], v[66:67]
	v_add_f32_e32 v66, v70, v71
	v_add_f32_e32 v67, v68, v69
	s_nop 0
	v_add_f32_dpp v66, v66, v66 quad_perm:[1,0,3,2] row_mask:0xf bank_mask:0xf bound_ctrl:1
	v_add_f32_dpp v67, v67, v67 quad_perm:[1,0,3,2] row_mask:0xf bank_mask:0xf bound_ctrl:1
	s_nop 0
	v_add_f32_dpp v66, v66, v66 quad_perm:[2,3,0,1] row_mask:0xf bank_mask:0xf bound_ctrl:1
	v_add_f32_dpp v68, v67, v67 quad_perm:[2,3,0,1] row_mask:0xf bank_mask:0xf bound_ctrl:1
	s_nop 0
	v_add_f32_dpp v66, v66, v66 row_half_mirror row_mask:0xf bank_mask:0xf bound_ctrl:1
	s_waitcnt lgkmcnt(13)
	v_mov_b32_e32 v67, v0
	s_waitcnt lgkmcnt(12)
	v_pk_mul_f32 v[70:71], v[98:99], v[66:67]
	v_add_f32_dpp v67, v68, v68 row_half_mirror row_mask:0xf bank_mask:0xf bound_ctrl:1
	v_add_f32_e32 v67, v70, v67
	s_add_i32 s20, s2, s46
	v_add_f32_e32 v67, v71, v67
	s_ashr_i32 s21, s20, 31
	v_bfe_u32 v68, v67, 16, 1
	s_lshl_b64 s[20:21], s[20:21], 9
	v_add3_u32 v67, v67, v68, s28
	v_lshl_add_u64 v[68:69], v[92:93], 0, s[20:21]
	global_store_short_d16_hi v[68:69], v67, off
	s_branch .LBB0_858

.LBB0_868:
	v_pk_mul_f32 v[50:51], v[50:51], v[84:85]
	v_pk_mul_f32 v[46:47], v[46:47], v[88:89]
	s_waitcnt lgkmcnt(14)
	v_pk_fma_f32 v[50:51], v[66:67], v[62:63], v[50:51] op_sel_hi:[0,1,1]
	v_pk_fma_f32 v[46:47], v[66:67], v[58:59], v[46:47] op_sel_hi:[0,1,1]
	s_waitcnt lgkmcnt(13)
	v_pk_fma_f32 v[84:85], v[0:1], v[54:55], v[50:51] op_sel_hi:[0,1,1]
	v_pk_mul_f32 v[50:51], v[52:53], v[86:87]
	v_pk_fma_f32 v[88:89], v[0:1], v[42:43], v[46:47] op_sel_hi:[0,1,1]
	v_pk_mul_f32 v[42:43], v[48:49], v[90:91]
	v_pk_fma_f32 v[50:51], v[66:67], v[64:65], v[50:51] op_sel_hi:[0,1,1]
	v_pk_fma_f32 v[42:43], v[66:67], v[60:61], v[42:43] op_sel_hi:[0,1,1]
	s_add_i32 s18, s18, s3
	s_add_i32 s7, s7, 2
	s_addk_i32 s6, 0xc40
	v_pk_fma_f32 v[86:87], v[0:1], v[56:57], v[50:51] op_sel_hi:[0,1,1]
	s_cmp_gt_u32 s7, 13
	v_pk_fma_f32 v[90:91], v[0:1], v[44:45], v[42:43] op_sel_hi:[0,1,1]
	s_cbranch_scc1 .LBB0_852
.LBB0_869:
	s_waitcnt lgkmcnt(0)
	v_mov_b32_e32 v95, v96
	v_add_u32_e32 v96, s6, v100
	ds_read_b128 v[70:73], v96 offset:26656
	ds_read_b128 v[66:69], v96 offset:26672
	ds_read_b128 v[50:53], v96 offset:26912
	ds_read_b128 v[46:49], v96 offset:26928
	ds_read_b128 v[54:57], v96 offset:27168
	ds_read_b128 v[42:45], v96 offset:27184
	ds_read_b128 v[78:81], v96 offset:27424
	ds_read_b128 v[74:77], v96 offset:27440
	ds_read_b128 v[62:65], v96 offset:27680
	ds_read_b128 v[58:61], v96 offset:27696
	v_pk_fma_f32 v[34:35], v[84:85], v[34:35], 0 op_sel_hi:[1,1,0]
	v_pk_fma_f32 v[22:23], v[84:85], v[22:23], 0 op_sel_hi:[1,1,0]
	v_pk_fma_f32 v[34:35], v[86:87], v[36:37], v[34:35]
	v_pk_fma_f32 v[22:23], v[86:87], v[24:25], v[22:23]
	v_add_u32_e32 v103, s6, v102
	v_mov_b32_e32 v98, s6
	v_pk_fma_f32 v[24:25], v[88:89], v[38:39], v[34:35]
	v_pk_fma_f32 v[18:19], v[88:89], v[18:19], v[22:23]
	ds_read_b32 v0, v103 offset:27936
	ds_read_b64 v[98:99], v98 offset:28192
	v_pk_fma_f32 v[22:23], v[90:91], v[40:41], v[24:25]
	v_pk_fma_f32 v[20:21], v[90:91], v[20:21], v[18:19]
	v_add_f32_e32 v18, v22, v23
	v_add_f32_e32 v19, v20, v21
	s_nop 0
	v_add_f32_dpp v18, v18, v18 quad_perm:[1,0,3,2] row_mask:0xf bank_mask:0xf bound_ctrl:1
	v_add_f32_dpp v19, v19, v19 quad_perm:[1,0,3,2] row_mask:0xf bank_mask:0xf bound_ctrl:1
	s_nop 0
	v_add_f32_dpp v18, v18, v18 quad_perm:[2,3,0,1] row_mask:0xf bank_mask:0xf bound_ctrl:1
	v_add_f32_dpp v19, v19, v19 quad_perm:[2,3,0,1] row_mask:0xf bank_mask:0xf bound_ctrl:1
	s_nop 0
	v_add_f32_dpp v18, v18, v18 row_half_mirror row_mask:0xf bank_mask:0xf bound_ctrl:1
	v_mov_b32_e32 v22, v97
	v_mov_b32_e32 v23, v18
	v_pk_mul_f32 v[22:23], v[22:23], v[94:95]
	v_add_f32_dpp v19, v19, v19 row_half_mirror row_mask:0xf bank_mask:0xf bound_ctrl:1
	v_add_f32_e32 v19, v23, v19
	v_add_f32_e32 v19, v22, v19
	s_ashr_i32 s19, s18, 31
	v_bfe_u32 v20, v19, 16, 1
	s_lshl_b64 s[10:11], s[18:19], 9
	v_add3_u32 v19, v19, v20, s28
	v_lshl_add_u64 v[20:21], v[92:93], 0, s[10:11]
	global_store_short_d16_hi v[20:21], v19, off
.LBB0_871:
	v_pk_mul_f32 v[2:3], v[84:85], v[2:3]
	s_nop 0
	v_pk_fma_f32 v[2:3], v[18:19], v[26:27], v[2:3] op_sel_hi:[0,1,1]
	v_pk_fma_f32 v[84:85], v[94:95], v[10:11], v[2:3] op_sel_hi:[0,1,1]
	v_pk_mul_f32 v[2:3], v[86:87], v[4:5]
	s_waitcnt lgkmcnt(5)
	v_pk_fma_f32 v[78:79], v[84:85], v[78:79], 0 op_sel_hi:[1,1,0]
	v_pk_fma_f32 v[2:3], v[18:19], v[28:29], v[2:3] op_sel_hi:[0,1,1]
	v_pk_fma_f32 v[86:87], v[94:95], v[12:13], v[2:3] op_sel_hi:[0,1,1]
	v_pk_mul_f32 v[2:3], v[88:89], v[6:7]
	v_pk_fma_f32 v[70:71], v[84:85], v[70:71], 0 op_sel_hi:[1,1,0]
	v_pk_fma_f32 v[2:3], v[18:19], v[30:31], v[2:3] op_sel_hi:[0,1,1]
	v_pk_fma_f32 v[88:89], v[94:95], v[14:15], v[2:3] op_sel_hi:[0,1,1]
	v_pk_mul_f32 v[2:3], v[90:91], v[8:9]
	v_pk_fma_f32 v[78:79], v[86:87], v[80:81], v[78:79]
	v_pk_fma_f32 v[2:3], v[18:19], v[32:33], v[2:3] op_sel_hi:[0,1,1]
	v_pk_fma_f32 v[90:91], v[94:95], v[16:17], v[2:3] op_sel_hi:[0,1,1]
	ds_read_b128 v[22:25], v96 offset:28224
	ds_read_b128 v[18:21], v96 offset:28240
	ds_read_b128 v[2:5], v96 offset:28480
	ds_read_b128 v[6:9], v96 offset:28496
	ds_read_b128 v[10:13], v96 offset:28736
	ds_read_b128 v[14:17], v96 offset:28752
	ds_read_b128 v[34:37], v96 offset:28992
	ds_read_b128 v[38:41], v96 offset:29008
	ds_read_b128 v[26:29], v96 offset:29248
	ds_read_b128 v[30:33], v96 offset:29264
	v_pk_fma_f32 v[70:71], v[86:87], v[72:73], v[70:71]
	s_waitcnt lgkmcnt(14)
	v_pk_fma_f32 v[72:73], v[88:89], v[74:75], v[78:79]
	v_pk_fma_f32 v[66:67], v[88:89], v[66:67], v[70:71]
	v_mov_b32_e32 v95, s6
	ds_read_b32 v94, v103 offset:29504
	ds_read_b64 v[96:97], v95 offset:29760
	v_pk_fma_f32 v[70:71], v[90:91], v[76:77], v[72:73]
	v_pk_fma_f32 v[68:69], v[90:91], v[68:69], v[66:67]
	v_add_f32_e32 v66, v70, v71
	v_add_f32_e32 v67, v68, v69
	s_nop 0
	v_add_f32_dpp v66, v66, v66 quad_perm:[1,0,3,2] row_mask:0xf bank_mask:0xf bound_ctrl:1
	v_add_f32_dpp v67, v67, v67 quad_perm:[1,0,3,2] row_mask:0xf bank_mask:0xf bound_ctrl:1
	s_nop 0
	v_add_f32_dpp v66, v66, v66 quad_perm:[2,3,0,1] row_mask:0xf bank_mask:0xf bound_ctrl:1
	v_add_f32_dpp v68, v67, v67 quad_perm:[2,3,0,1] row_mask:0xf bank_mask:0xf bound_ctrl:1
	s_nop 0
	v_add_f32_dpp v66, v66, v66 row_half_mirror row_mask:0xf bank_mask:0xf bound_ctrl:1
	s_waitcnt lgkmcnt(13)
	v_mov_b32_e32 v67, v0
	s_waitcnt lgkmcnt(12)
	v_pk_mul_f32 v[70:71], v[98:99], v[66:67]
	v_add_f32_dpp v67, v68, v68 row_half_mirror row_mask:0xf bank_mask:0xf bound_ctrl:1
	v_add_f32_e32 v67, v70, v67
	s_add_i32 s10, s2, s18
	v_add_f32_e32 v67, v71, v67
	s_ashr_i32 s11, s10, 31
	v_bfe_u32 v68, v67, 16, 1
	s_lshl_b64 s[10:11], s[10:11], 9
	v_add3_u32 v67, v67, v68, s28
	v_lshl_add_u64 v[68:69], v[92:93], 0, s[10:11]
	global_store_short_d16_hi v[68:69], v67, off
	s_branch .LBB0_868

.LBB0_905:
	v_pk_mul_f32 v[54:55], v[70:71], v[74:75] op_sel_hi:[0,1]
	v_pk_fma_f32 v[74:75], v[50:51], v[0:1], v[54:55] op_sel_hi:[1,0,1]
	v_pk_mul_f32 v[50:51], v[70:71], v[78:79] op_sel_hi:[0,1]
	v_pk_fma_f32 v[78:79], v[52:53], v[0:1], v[50:51] op_sel_hi:[1,0,1]
	v_pk_mul_f32 v[50:51], v[70:71], v[80:81] op_sel_hi:[0,1]
	v_pk_fma_f32 v[80:81], v[46:47], v[0:1], v[50:51] op_sel_hi:[1,0,1]
	v_pk_mul_f32 v[46:47], v[70:71], v[82:83] op_sel_hi:[0,1]
	v_pk_fma_f32 v[82:83], v[48:49], v[0:1], v[46:47] op_sel_hi:[1,0,1]
	v_pk_mul_f32 v[46:47], v[70:71], v[84:85] op_sel_hi:[0,1]
	v_pk_fma_f32 v[84:85], v[42:43], v[0:1], v[46:47] op_sel_hi:[1,0,1]
	v_pk_mul_f32 v[42:43], v[70:71], v[86:87] op_sel_hi:[0,1]
	v_pk_fma_f32 v[86:87], v[44:45], v[0:1], v[42:43] op_sel_hi:[1,0,1]
	v_pk_mul_f32 v[42:43], v[70:71], v[88:89] op_sel_hi:[0,1]
	v_pk_fma_f32 v[88:89], v[38:39], v[0:1], v[42:43] op_sel_hi:[1,0,1]
	v_pk_mul_f32 v[38:39], v[70:71], v[90:91] op_sel_hi:[0,1]
	s_add_i32 s18, s18, s25
	s_add_i32 s10, s10, 2
	s_addk_i32 s7, 0x640
	s_cmp_gt_u32 s10, 13
	v_pk_fma_f32 v[90:91], v[40:41], v[0:1], v[38:39] op_sel_hi:[1,0,1]
	s_cbranch_scc1 .LBB0_910
.LBB0_906:
	s_waitcnt lgkmcnt(5)
	v_pk_fma_f32 v[100:101], v[74:75], v[2:3], 0 op_sel_hi:[1,1,0]
	s_waitcnt lgkmcnt(0)
	v_mov_b32_e32 v37, v34
	v_add_u32_e32 v34, s7, v94
	v_pk_fma_f32 v[30:31], v[74:75], v[30:31], 0 op_sel_hi:[1,1,0]
	v_pk_fma_f32 v[100:101], v[78:79], v[4:5], v[100:101]
	ds_read_b128 v[66:69], v34 offset:800
	ds_read_b128 v[62:65], v34 offset:816
	ds_read_b128 v[58:61], v34 offset:832
	ds_read_b128 v[54:57], v34 offset:848
	ds_read_b128 v[50:53], v34 offset:1056
	ds_read_b128 v[46:49], v34 offset:1072
	ds_read_b128 v[42:45], v34 offset:1088
	ds_read_b128 v[38:41], v34 offset:1104
	v_pk_fma_f32 v[30:31], v[78:79], v[32:33], v[30:31]
	v_pk_fma_f32 v[32:33], v[80:81], v[6:7], v[100:101]
	v_pk_fma_f32 v[26:27], v[80:81], v[26:27], v[30:31]
	v_pk_fma_f32 v[30:31], v[82:83], v[8:9], v[32:33]
	v_pk_fma_f32 v[26:27], v[82:83], v[28:29], v[26:27]
	s_waitcnt lgkmcnt(9)
	v_pk_fma_f32 v[28:29], v[84:85], v[14:15], v[30:31]
	v_pk_fma_f32 v[22:23], v[84:85], v[22:23], v[26:27]
	v_pk_fma_f32 v[26:27], v[86:87], v[16:17], v[28:29]
	v_pk_fma_f32 v[22:23], v[86:87], v[24:25], v[22:23]
	s_waitcnt lgkmcnt(8)
	v_pk_fma_f32 v[24:25], v[88:89], v[10:11], v[26:27]
	v_add_u32_e32 v98, s7, v97
	v_mov_b32_e32 v70, s7
	v_pk_fma_f32 v[18:19], v[88:89], v[18:19], v[22:23]
	v_pk_fma_f32 v[22:23], v[90:91], v[12:13], v[24:25]
	ds_read_b32 v0, v98
	ds_read_b96 v[70:72], v70 offset:1568
	v_pk_fma_f32 v[18:19], v[90:91], v[20:21], v[18:19]
	v_add_f32_e32 v20, v22, v23
	v_add_f32_e32 v18, v18, v19
	s_nop 0
	v_add_f32_dpp v20, v20, v20 quad_perm:[1,0,3,2] row_mask:0xf bank_mask:0xf bound_ctrl:1
	v_add_f32_dpp v19, v18, v18 quad_perm:[1,0,3,2] row_mask:0xf bank_mask:0xf bound_ctrl:1
	s_nop 0
	v_add_f32_dpp v20, v20, v20 quad_perm:[2,3,0,1] row_mask:0xf bank_mask:0xf bound_ctrl:1
	v_fma_f32 v18, -v37, v20, v73
	v_mul_f32_e32 v18, v35, v18
	v_add_f32_dpp v19, v19, v19 quad_perm:[2,3,0,1] row_mask:0xf bank_mask:0xf bound_ctrl:1
	v_mul_f32_e32 v20, v37, v19
	v_pk_fma_f32 v[20:21], v[36:37], v[18:19], v[20:21] op_sel_hi:[1,1,0]
	s_ashr_i32 s19, s18, 31
	v_bfe_u32 v19, v20, 16, 1
	s_lshl_b64 s[20:21], s[18:19], 9
	v_add3_u32 v19, v20, v19, s28
	v_lshl_add_u64 v[20:21], v[92:93], 0, s[20:21]
	global_store_short_d16_hi v[20:21], v19, off
.LBB0_908:
	v_pk_mul_f32 v[20:21], v[74:75], v[36:37] op_sel:[0,1]
	s_nop 0
	v_pk_fma_f32 v[74:75], v[2:3], v[18:19], v[20:21] op_sel_hi:[1,0,1]
	v_pk_mul_f32 v[2:3], v[78:79], v[36:37] op_sel:[0,1]
	s_waitcnt lgkmcnt(9)
	v_pk_fma_f32 v[66:67], v[74:75], v[66:67], 0 op_sel_hi:[1,1,0]
	v_pk_fma_f32 v[78:79], v[4:5], v[18:19], v[2:3] op_sel_hi:[1,0,1]
	v_pk_mul_f32 v[2:3], v[80:81], v[36:37] op_sel:[0,1]
	v_pk_fma_f32 v[66:67], v[78:79], v[68:69], v[66:67]
	v_pk_fma_f32 v[80:81], v[6:7], v[18:19], v[2:3] op_sel_hi:[1,0,1]
	v_pk_mul_f32 v[2:3], v[82:83], v[36:37] op_sel:[0,1]
	s_waitcnt lgkmcnt(8)
	v_pk_fma_f32 v[62:63], v[80:81], v[62:63], v[66:67]
	v_pk_fma_f32 v[82:83], v[8:9], v[18:19], v[2:3] op_sel_hi:[1,0,1]
	v_pk_mul_f32 v[2:3], v[84:85], v[36:37] op_sel:[0,1]
	v_pk_fma_f32 v[62:63], v[82:83], v[64:65], v[62:63]
	v_pk_fma_f32 v[84:85], v[14:15], v[18:19], v[2:3] op_sel_hi:[1,0,1]
	v_pk_mul_f32 v[2:3], v[86:87], v[36:37] op_sel:[0,1]
	s_waitcnt lgkmcnt(7)
	v_pk_fma_f32 v[58:59], v[84:85], v[58:59], v[62:63]
	v_pk_fma_f32 v[86:87], v[16:17], v[18:19], v[2:3] op_sel_hi:[1,0,1]
	v_pk_mul_f32 v[2:3], v[88:89], v[36:37] op_sel:[0,1]
	v_pk_fma_f32 v[58:59], v[86:87], v[60:61], v[58:59]
	v_pk_fma_f32 v[88:89], v[10:11], v[18:19], v[2:3] op_sel_hi:[1,0,1]
	v_pk_mul_f32 v[2:3], v[90:91], v[36:37] op_sel:[0,1]
	s_waitcnt lgkmcnt(6)
	v_pk_fma_f32 v[54:55], v[88:89], v[54:55], v[58:59]
	v_pk_fma_f32 v[90:91], v[12:13], v[18:19], v[2:3] op_sel_hi:[1,0,1]
	ds_read_b128 v[30:33], v34 offset:1600
	ds_read_b128 v[26:29], v34 offset:1616
	ds_read_b128 v[22:25], v34 offset:1632
	ds_read_b128 v[18:21], v34 offset:1648
	ds_read_b128 v[2:5], v34 offset:1856
	ds_read_b128 v[6:9], v34 offset:1872
	ds_read_b128 v[14:17], v34 offset:1888
	ds_read_b128 v[10:13], v34 offset:1904
	v_mov_b32_e32 v34, s7
	ds_read_b32 v73, v98 offset:800
	ds_read_b96 v[34:36], v34 offset:2368
	s_waitcnt lgkmcnt(14)
	v_pk_fma_f32 v[98:99], v[74:75], v[50:51], 0 op_sel_hi:[1,1,0]
	v_pk_fma_f32 v[54:55], v[90:91], v[56:57], v[54:55]
	v_pk_fma_f32 v[98:99], v[78:79], v[52:53], v[98:99]
	s_nop 0
	v_pk_fma_f32 v[68:69], v[80:81], v[46:47], v[98:99]
	s_nop 0
	v_pk_fma_f32 v[66:67], v[82:83], v[48:49], v[68:69]
	s_waitcnt lgkmcnt(13)
	v_pk_fma_f32 v[64:65], v[84:85], v[42:43], v[66:67]
	s_nop 0
	v_pk_fma_f32 v[62:63], v[86:87], v[44:45], v[64:65]
	s_waitcnt lgkmcnt(12)
	v_pk_fma_f32 v[60:61], v[88:89], v[38:39], v[62:63]
	s_nop 0
	v_pk_fma_f32 v[58:59], v[90:91], v[40:41], v[60:61]
	s_nop 0
	v_add_f32_e32 v37, v58, v59
	s_nop 1
	v_add_f32_dpp v37, v37, v37 quad_perm:[1,0,3,2] row_mask:0xf bank_mask:0xf bound_ctrl:1
	s_nop 1
	v_add_f32_dpp v56, v37, v37 quad_perm:[2,3,0,1] row_mask:0xf bank_mask:0xf bound_ctrl:1
	v_add_f32_e32 v37, v54, v55
	s_waitcnt lgkmcnt(10)
	v_fma_f32 v0, -v70, v56, v0
	v_mul_f32_e32 v0, v71, v0
	v_add_f32_dpp v37, v37, v37 quad_perm:[1,0,3,2] row_mask:0xf bank_mask:0xf bound_ctrl:1
	s_nop 1
	v_add_f32_dpp v54, v37, v37 quad_perm:[2,3,0,1] row_mask:0xf bank_mask:0xf bound_ctrl:1
	v_mov_b32_e32 v71, v72
	v_mov_b32_e32 v55, v0
	v_mul_f32_e32 v56, v72, v0
	s_add_i32 s20, s24, s18
	v_pk_fma_f32 v[54:55], v[70:71], v[54:55], v[56:57] op_sel_hi:[1,1,0]
	s_ashr_i32 s21, s20, 31
	v_bfe_u32 v37, v54, 16, 1
	s_lshl_b64 s[20:21], s[20:21], 9
	v_add3_u32 v37, v54, v37, s28
	v_lshl_add_u64 v[54:55], v[92:93], 0, s[20:21]
	global_store_short_d16_hi v[54:55], v37, off
	s_branch .LBB0_905

.LBB0_915:
	v_pk_mul_f32 v[54:55], v[70:71], v[74:75] op_sel_hi:[0,1]
	v_pk_fma_f32 v[74:75], v[50:51], v[0:1], v[54:55] op_sel_hi:[1,0,1]
	v_pk_mul_f32 v[50:51], v[70:71], v[78:79] op_sel_hi:[0,1]
	v_pk_fma_f32 v[78:79], v[52:53], v[0:1], v[50:51] op_sel_hi:[1,0,1]
	v_pk_mul_f32 v[50:51], v[70:71], v[80:81] op_sel_hi:[0,1]
	v_pk_fma_f32 v[80:81], v[46:47], v[0:1], v[50:51] op_sel_hi:[1,0,1]
	v_pk_mul_f32 v[46:47], v[70:71], v[82:83] op_sel_hi:[0,1]
	v_pk_fma_f32 v[82:83], v[48:49], v[0:1], v[46:47] op_sel_hi:[1,0,1]
	v_pk_mul_f32 v[46:47], v[70:71], v[84:85] op_sel_hi:[0,1]
	v_pk_fma_f32 v[84:85], v[42:43], v[0:1], v[46:47] op_sel_hi:[1,0,1]
	v_pk_mul_f32 v[42:43], v[70:71], v[86:87] op_sel_hi:[0,1]
	v_pk_fma_f32 v[86:87], v[44:45], v[0:1], v[42:43] op_sel_hi:[1,0,1]
	v_pk_mul_f32 v[42:43], v[70:71], v[88:89] op_sel_hi:[0,1]
	v_pk_fma_f32 v[88:89], v[38:39], v[0:1], v[42:43] op_sel_hi:[1,0,1]
	v_pk_mul_f32 v[38:39], v[70:71], v[90:91] op_sel_hi:[0,1]
	s_add_i32 s16, s16, s25
	s_add_i32 s6, s6, 2
	s_addk_i32 s7, 0x640
	s_cmp_gt_u32 s6, 13
	v_pk_fma_f32 v[90:91], v[40:41], v[0:1], v[38:39] op_sel_hi:[1,0,1]
	s_cbranch_scc1 .LBB0_899
.LBB0_916:
	s_waitcnt lgkmcnt(5)
	v_pk_fma_f32 v[100:101], v[74:75], v[2:3], 0 op_sel_hi:[1,1,0]
	s_waitcnt lgkmcnt(0)
	v_mov_b32_e32 v37, v34
	v_add_u32_e32 v34, s7, v94
	v_pk_fma_f32 v[30:31], v[74:75], v[30:31], 0 op_sel_hi:[1,1,0]
	v_pk_fma_f32 v[100:101], v[78:79], v[4:5], v[100:101]
	ds_read_b128 v[66:69], v34
	ds_read_b128 v[62:65], v34 offset:16
	ds_read_b128 v[58:61], v34 offset:32
	ds_read_b128 v[54:57], v34 offset:48
	ds_read_b128 v[50:53], v34 offset:256
	ds_read_b128 v[46:49], v34 offset:272
	ds_read_b128 v[42:45], v34 offset:288
	ds_read_b128 v[38:41], v34 offset:304
	v_pk_fma_f32 v[30:31], v[78:79], v[32:33], v[30:31]
	v_pk_fma_f32 v[32:33], v[80:81], v[6:7], v[100:101]
	v_pk_fma_f32 v[26:27], v[80:81], v[26:27], v[30:31]
	v_pk_fma_f32 v[30:31], v[82:83], v[8:9], v[32:33]
	v_pk_fma_f32 v[26:27], v[82:83], v[28:29], v[26:27]
	s_waitcnt lgkmcnt(9)
	v_pk_fma_f32 v[28:29], v[84:85], v[14:15], v[30:31]
	v_pk_fma_f32 v[22:23], v[84:85], v[22:23], v[26:27]
	v_pk_fma_f32 v[26:27], v[86:87], v[16:17], v[28:29]
	v_pk_fma_f32 v[22:23], v[86:87], v[24:25], v[22:23]
	s_waitcnt lgkmcnt(8)
	v_pk_fma_f32 v[24:25], v[88:89], v[10:11], v[26:27]
	v_add_u32_e32 v98, s7, v96
	v_mov_b32_e32 v70, s7
	v_pk_fma_f32 v[18:19], v[88:89], v[18:19], v[22:23]
	v_pk_fma_f32 v[22:23], v[90:91], v[12:13], v[24:25]
	ds_read_b32 v0, v98 offset:512
	ds_read_b96 v[70:72], v70 offset:768
	v_pk_fma_f32 v[18:19], v[90:91], v[20:21], v[18:19]
	v_add_f32_e32 v20, v22, v23
	v_add_f32_e32 v18, v18, v19
	s_nop 0
	v_add_f32_dpp v20, v20, v20 quad_perm:[1,0,3,2] row_mask:0xf bank_mask:0xf bound_ctrl:1
	v_add_f32_dpp v19, v18, v18 quad_perm:[1,0,3,2] row_mask:0xf bank_mask:0xf bound_ctrl:1
	s_nop 0
	v_add_f32_dpp v20, v20, v20 quad_perm:[2,3,0,1] row_mask:0xf bank_mask:0xf bound_ctrl:1
	v_fma_f32 v18, -v37, v20, v73
	v_mul_f32_e32 v18, v35, v18
	v_add_f32_dpp v19, v19, v19 quad_perm:[2,3,0,1] row_mask:0xf bank_mask:0xf bound_ctrl:1
	v_mul_f32_e32 v20, v37, v19
	v_pk_fma_f32 v[20:21], v[36:37], v[18:19], v[20:21] op_sel_hi:[1,1,0]
	s_ashr_i32 s17, s16, 31
	v_bfe_u32 v19, v20, 16, 1
	s_lshl_b64 s[10:11], s[16:17], 9
	v_add3_u32 v19, v20, v19, s28
	v_lshl_add_u64 v[20:21], v[92:93], 0, s[10:11]
	global_store_short_d16_hi v[20:21], v19, off
.LBB0_918:
	v_pk_mul_f32 v[20:21], v[74:75], v[36:37] op_sel:[0,1]
	s_nop 0
	v_pk_fma_f32 v[74:75], v[2:3], v[18:19], v[20:21] op_sel_hi:[1,0,1]
	v_pk_mul_f32 v[2:3], v[78:79], v[36:37] op_sel:[0,1]
	s_waitcnt lgkmcnt(9)
	v_pk_fma_f32 v[66:67], v[74:75], v[66:67], 0 op_sel_hi:[1,1,0]
	v_pk_fma_f32 v[78:79], v[4:5], v[18:19], v[2:3] op_sel_hi:[1,0,1]
	v_pk_mul_f32 v[2:3], v[80:81], v[36:37] op_sel:[0,1]
	v_pk_fma_f32 v[66:67], v[78:79], v[68:69], v[66:67]
	v_pk_fma_f32 v[80:81], v[6:7], v[18:19], v[2:3] op_sel_hi:[1,0,1]
	v_pk_mul_f32 v[2:3], v[82:83], v[36:37] op_sel:[0,1]
	s_waitcnt lgkmcnt(8)
	v_pk_fma_f32 v[62:63], v[80:81], v[62:63], v[66:67]
	v_pk_fma_f32 v[82:83], v[8:9], v[18:19], v[2:3] op_sel_hi:[1,0,1]
	v_pk_mul_f32 v[2:3], v[84:85], v[36:37] op_sel:[0,1]
	v_pk_fma_f32 v[62:63], v[82:83], v[64:65], v[62:63]
	v_pk_fma_f32 v[84:85], v[14:15], v[18:19], v[2:3] op_sel_hi:[1,0,1]
	v_pk_mul_f32 v[2:3], v[86:87], v[36:37] op_sel:[0,1]
	s_waitcnt lgkmcnt(7)
	v_pk_fma_f32 v[58:59], v[84:85], v[58:59], v[62:63]
	v_pk_fma_f32 v[86:87], v[16:17], v[18:19], v[2:3] op_sel_hi:[1,0,1]
	v_pk_mul_f32 v[2:3], v[88:89], v[36:37] op_sel:[0,1]
	v_pk_fma_f32 v[58:59], v[86:87], v[60:61], v[58:59]
	v_pk_fma_f32 v[88:89], v[10:11], v[18:19], v[2:3] op_sel_hi:[1,0,1]
	v_pk_mul_f32 v[2:3], v[90:91], v[36:37] op_sel:[0,1]
	s_waitcnt lgkmcnt(6)
	v_pk_fma_f32 v[54:55], v[88:89], v[54:55], v[58:59]
	v_pk_fma_f32 v[90:91], v[12:13], v[18:19], v[2:3] op_sel_hi:[1,0,1]
	ds_read_b128 v[30:33], v34 offset:800
	ds_read_b128 v[26:29], v34 offset:816
	ds_read_b128 v[22:25], v34 offset:832
	ds_read_b128 v[18:21], v34 offset:848
	ds_read_b128 v[2:5], v34 offset:1056
	ds_read_b128 v[6:9], v34 offset:1072
	ds_read_b128 v[14:17], v34 offset:1088
	ds_read_b128 v[10:13], v34 offset:1104
	v_mov_b32_e32 v34, s7
	ds_read_b32 v73, v98 offset:1312
	ds_read_b96 v[34:36], v34 offset:1568
	s_waitcnt lgkmcnt(14)
	v_pk_fma_f32 v[98:99], v[74:75], v[50:51], 0 op_sel_hi:[1,1,0]
	v_pk_fma_f32 v[54:55], v[90:91], v[56:57], v[54:55]
	v_pk_fma_f32 v[98:99], v[78:79], v[52:53], v[98:99]
	s_nop 0
	v_pk_fma_f32 v[68:69], v[80:81], v[46:47], v[98:99]
	s_nop 0
	v_pk_fma_f32 v[66:67], v[82:83], v[48:49], v[68:69]
	s_waitcnt lgkmcnt(13)
	v_pk_fma_f32 v[64:65], v[84:85], v[42:43], v[66:67]
	s_nop 0
	v_pk_fma_f32 v[62:63], v[86:87], v[44:45], v[64:65]
	s_waitcnt lgkmcnt(12)
	v_pk_fma_f32 v[60:61], v[88:89], v[38:39], v[62:63]
	s_nop 0
	v_pk_fma_f32 v[58:59], v[90:91], v[40:41], v[60:61]
	s_nop 0
	v_add_f32_e32 v37, v58, v59
	s_nop 1
	v_add_f32_dpp v37, v37, v37 quad_perm:[1,0,3,2] row_mask:0xf bank_mask:0xf bound_ctrl:1
	s_nop 1
	v_add_f32_dpp v56, v37, v37 quad_perm:[2,3,0,1] row_mask:0xf bank_mask:0xf bound_ctrl:1
	v_add_f32_e32 v37, v54, v55
	s_waitcnt lgkmcnt(10)
	v_fma_f32 v0, -v70, v56, v0
	v_mul_f32_e32 v0, v71, v0
	v_add_f32_dpp v37, v37, v37 quad_perm:[1,0,3,2] row_mask:0xf bank_mask:0xf bound_ctrl:1
	s_nop 1
	v_add_f32_dpp v54, v37, v37 quad_perm:[2,3,0,1] row_mask:0xf bank_mask:0xf bound_ctrl:1
	v_mov_b32_e32 v71, v72
	v_mov_b32_e32 v55, v0
	v_mul_f32_e32 v56, v72, v0
	s_add_i32 s10, s24, s16
	v_pk_fma_f32 v[54:55], v[70:71], v[54:55], v[56:57] op_sel_hi:[1,1,0]
	s_ashr_i32 s11, s10, 31
	v_bfe_u32 v37, v54, 16, 1
	s_lshl_b64 s[10:11], s[10:11], 9
	v_add3_u32 v37, v54, v37, s28
	v_lshl_add_u64 v[54:55], v[92:93], 0, s[10:11]
	global_store_short_d16_hi v[54:55], v37, off
	s_branch .LBB0_915
